# P3: output-address lane constants folded into the per-item pointers (12 fewer VALU per wave-chunk)
# speedup vs baseline: 1.0005x; 1.0005x over previous
.LBB0_590:
	v_lshl_add_u64 v[12:13], s[82:83], 0, v[8:9]
	s_mov_b32 s4, 0x100000
	v_add_co_u32_e32 v70, vcc, s4, v12
	v_lshl_add_u64 v[10:11], s[82:83], 0, v[6:7]
	s_mov_b32 s5, 0x101000
	v_addc_co_u32_e32 v71, vcc, 0, v13, vcc
	global_load_dword v3, v[10:11], off
	v_add_co_u32_e32 v102, vcc, s5, v12
	v_lshl_add_u64 v[74:75], s[82:83], 0, v[4:5]
	s_nop 0
	v_addc_co_u32_e32 v103, vcc, 0, v13, vcc
	global_load_dwordx4 v[10:13], v[102:103], off offset:-4096
	global_load_dwordx4 v[14:17], v[70:71], off offset:512
	global_load_dwordx4 v[50:53], v[70:71], off offset:32
	global_load_dwordx4 v[54:57], v[70:71], off offset:544
	global_load_dwordx4 v[58:61], v[70:71], off offset:64
	global_load_dwordx4 v[62:65], v[70:71], off offset:576
	global_load_dwordx4 v[66:69], v[70:71], off offset:96
	s_nop 0
	global_load_dwordx4 v[70:73], v[70:71], off offset:608
	s_nop 0
	global_load_dword v107, v[74:75], off
	s_nop 0
	global_load_dwordx4 v[74:77], v[102:103], off
	global_load_dwordx4 v[78:81], v[102:103], off offset:512
	global_load_dwordx4 v[82:85], v[102:103], off offset:32
	global_load_dwordx4 v[86:89], v[102:103], off offset:544
	global_load_dwordx4 v[90:93], v[102:103], off offset:64
	global_load_dwordx4 v[94:97], v[102:103], off offset:576
	global_load_dwordx4 v[98:101], v[102:103], off offset:96
	s_nop 0
	global_load_dwordx4 v[102:105], v[102:103], off offset:608
	s_add_i32 s11, s7, 1
	v_cvt_f32_u32_e32 v106, s7
	v_cvt_f32_u32_e32 v108, s11
	s_mov_b64 s[4:5], 0x2000
	v_lshl_add_u64 v[8:9], v[8:9], 0, s[4:5]
	v_mul_f32_e32 v109, v224, v106
	v_mul_f32_e32 v110, v224, v108
	v_cmp_gt_f32_e32 vcc, s0, v109
	v_cmp_gt_f32_e64 s[4:5], s0, v110
	v_lshl_add_u64 v[4:5], v[4:5], 0, s[94:95]
	v_cndmask_b32_e32 v109, 0, v220, vcc
	v_cndmask_b32_e64 v110, 0, v220, s[4:5]
	v_fmac_f32_e32 v109, v224, v106
	v_fmac_f32_e32 v110, v224, v108
	v_exp_f32_e32 v106, v109
	v_exp_f32_e32 v108, v110
	s_and_b64 s[4:5], s[4:5], exec
	s_cselect_b32 s11, 0xffffffc0, 0
	s_and_b64 s[4:5], vcc, exec
	s_cselect_b32 s4, 0xffffffc0, 0
	v_ldexp_f32 v109, v106, s4
	v_ldexp_f32 v106, v108, s11
	s_add_i32 s7, s7, -2
	v_lshl_add_u64 v[6:7], v[6:7], 0, s[94:95]
	s_cmp_eq_u32 s7, -2
	s_waitcnt vmcnt(0)
	v_mul_f32_e32 v106, v3, v106
	v_pk_fma_f32 v[10:11], v[106:107], v[10:11], v[18:19] op_sel_hi:[0,1,1]
	v_pk_fma_f32 v[14:15], v[106:107], v[14:15], v[34:35] op_sel_hi:[0,1,1]
	v_pk_fma_f32 v[12:13], v[106:107], v[12:13], v[20:21] op_sel_hi:[0,1,1]
	v_pk_fma_f32 v[16:17], v[106:107], v[16:17], v[36:37] op_sel_hi:[0,1,1]
	v_pk_fma_f32 v[22:23], v[106:107], v[50:51], v[22:23] op_sel_hi:[0,1,1]
	v_pk_fma_f32 v[38:39], v[106:107], v[54:55], v[38:39] op_sel_hi:[0,1,1]
	v_pk_fma_f32 v[24:25], v[106:107], v[52:53], v[24:25] op_sel_hi:[0,1,1]
	v_pk_fma_f32 v[40:41], v[106:107], v[56:57], v[40:41] op_sel_hi:[0,1,1]
	v_pk_fma_f32 v[26:27], v[106:107], v[58:59], v[26:27] op_sel_hi:[0,1,1]
	v_pk_fma_f32 v[42:43], v[106:107], v[62:63], v[42:43] op_sel_hi:[0,1,1]
	v_pk_fma_f32 v[28:29], v[106:107], v[60:61], v[28:29] op_sel_hi:[0,1,1]
	v_pk_fma_f32 v[44:45], v[106:107], v[64:65], v[44:45] op_sel_hi:[0,1,1]
	v_pk_fma_f32 v[30:31], v[106:107], v[66:67], v[30:31] op_sel_hi:[0,1,1]
	v_pk_fma_f32 v[46:47], v[106:107], v[70:71], v[46:47] op_sel_hi:[0,1,1]
	v_pk_fma_f32 v[32:33], v[106:107], v[68:69], v[32:33] op_sel_hi:[0,1,1]
	v_pk_fma_f32 v[48:49], v[106:107], v[72:73], v[48:49] op_sel_hi:[0,1,1]
	v_mul_f32_e32 v50, v107, v109
	v_pk_fma_f32 v[18:19], v[50:51], v[74:75], v[10:11] op_sel_hi:[0,1,1]
	v_pk_fma_f32 v[34:35], v[50:51], v[78:79], v[14:15] op_sel_hi:[0,1,1]
	v_pk_fma_f32 v[20:21], v[50:51], v[76:77], v[12:13] op_sel_hi:[0,1,1]
	v_pk_fma_f32 v[36:37], v[50:51], v[80:81], v[16:17] op_sel_hi:[0,1,1]
	v_pk_fma_f32 v[22:23], v[50:51], v[82:83], v[22:23] op_sel_hi:[0,1,1]
	v_pk_fma_f32 v[38:39], v[50:51], v[86:87], v[38:39] op_sel_hi:[0,1,1]
	v_pk_fma_f32 v[24:25], v[50:51], v[84:85], v[24:25] op_sel_hi:[0,1,1]
	v_pk_fma_f32 v[40:41], v[50:51], v[88:89], v[40:41] op_sel_hi:[0,1,1]
	v_pk_fma_f32 v[26:27], v[50:51], v[90:91], v[26:27] op_sel_hi:[0,1,1]
	v_pk_fma_f32 v[42:43], v[50:51], v[94:95], v[42:43] op_sel_hi:[0,1,1]
	v_pk_fma_f32 v[28:29], v[50:51], v[92:93], v[28:29] op_sel_hi:[0,1,1]
	v_pk_fma_f32 v[44:45], v[50:51], v[96:97], v[44:45] op_sel_hi:[0,1,1]
	v_pk_fma_f32 v[30:31], v[50:51], v[98:99], v[30:31] op_sel_hi:[0,1,1]
	v_pk_fma_f32 v[46:47], v[50:51], v[102:103], v[46:47] op_sel_hi:[0,1,1]
	v_pk_fma_f32 v[32:33], v[50:51], v[100:101], v[32:33] op_sel_hi:[0,1,1]
	v_pk_fma_f32 v[48:49], v[50:51], v[104:105], v[48:49] op_sel_hi:[0,1,1]
	s_cbranch_scc0 .LBB0_590
	s_ashr_i32 s52, s84, 5
	s_ashr_i32 s53, s52, 31
	s_lshl_b64 s[4:5], s[52:53], 12
	v_mov_b32_e32 v5, s5
	v_or_b32_e32 v4, s4, v154
	v_mov_b32_e32 v9, s5
	v_or_b32_e32 v8, s4, v156
	v_readlane_b32 s4, v255, 15
	v_lshlrev_b64 v[4:5], 11, v[4:5]
	v_readlane_b32 s5, v255, 16
	v_lshl_add_u64 v[6:7], s[86:87], 0, v[4:5]
	s_mov_b32 s7, s91
	v_lshl_add_u64 v[4:5], s[4:5], 0, v[4:5]
	v_lshlrev_b64 v[8:9], 12, v[8:9]
	v_lshl_add_u64 v[4:5], v[4:5], 0, s[6:7]
	v_mov_b32_e32 v169, v2
	s_and_b32 s11, s84, 7
	v_lshl_add_u64 v[16:17], v[4:5], 0, v[168:169]
	v_lshl_add_u64 v[4:5], s[88:89], 0, v[8:9]
	s_mov_b32 s55, s91
	v_lshl_add_u64 v[4:5], v[4:5], 0, s[54:55]
	s_lshl_b32 s4, s11, 7
	s_mov_b32 s5, s91
	v_lshl_add_u64 v[56:57], v[4:5], 0, s[4:5]
	s_mov_b32 s4, 0x10000
	v_lshl_add_u64 v[6:7], v[6:7], 0, s[6:7]
	v_add_co_u32_e32 v8, vcc, s4, v16
	v_lshl_add_u64 v[54:55], v[6:7], 0, v[168:169]
	s_nop 0
	v_addc_co_u32_e32 v9, vcc, 0, v17, vcc
	v_add_co_u32_e32 v58, vcc, s4, v54
	s_mov_b32 s4, 0x20000
	s_nop 0
	v_addc_co_u32_e32 v59, vcc, 0, v55, vcc
	v_add_co_u32_e32 v12, vcc, s4, v16
	global_load_dwordx4 v[114:117], v[16:17], off
	global_load_dwordx4 v[4:7], v[54:55], off
	v_addc_co_u32_e32 v13, vcc, 0, v17, vcc
	v_add_co_u32_e32 v60, vcc, s4, v54
	s_mov_b32 s4, 0x30000
	s_nop 0
	v_addc_co_u32_e32 v61, vcc, 0, v55, vcc
	v_add_co_u32_e32 v16, vcc, s4, v16
	v_mov_b32_e32 v171, v2
	s_nop 0
	v_addc_co_u32_e32 v17, vcc, 0, v17, vcc
	v_add_co_u32_e32 v62, vcc, s4, v54
	global_load_dwordx4 v[118:121], v[8:9], off
	s_nop 0
	global_load_dwordx4 v[8:11], v[58:59], off
	global_load_dwordx4 v[134:137], v[12:13], off
	s_nop 0
	global_load_dwordx4 v[12:15], v[60:61], off
	v_addc_co_u32_e32 v63, vcc, 0, v55, vcc
	global_load_dwordx4 v[142:145], v[16:17], off
	global_load_dwordx4 v[50:53], v[62:63], off
	v_lshl_add_u64 v[16:17], v[56:57], 0, v[170:171]
	s_mov_b32 s4, 0x40000
	v_add_co_u32_e32 v56, vcc, s4, v16
	s_lshl_b32 s4, s90, 6
	s_nop 0
	v_addc_co_u32_e32 v57, vcc, 0, v17, vcc
	global_load_dwordx4 v[122:125], v[16:17], off
	global_load_dwordx4 v[126:129], v[56:57], off
	s_add_i32 s4, s4, 0
	s_add_i32 s4, s4, 0x15800
	v_or_b32_e32 v16, s38, v1
	v_mov_b32_e32 v17, s4
	s_movk_i32 s4, 0x210
	v_mad_u32_u24 v16, v16, s4, v17
	v_add_u32_e32 v169, v16, v157
	v_cvt_pk_bf16_f32 v16, v18, v19
	v_cvt_pk_bf16_f32 v17, v20, v21
	v_cvt_pk_bf16_f32 v56, v22, v23
	v_cvt_pk_bf16_f32 v57, v24, v25
	ds_write2_b64 v169, v[16:17], v[56:57] offset1:2
	v_cvt_pk_bf16_f32 v16, v26, v27
	v_cvt_pk_bf16_f32 v17, v28, v29
	v_cvt_pk_bf16_f32 v56, v30, v31
	v_cvt_pk_bf16_f32 v57, v32, v33
	ds_write2_b64 v169, v[16:17], v[56:57] offset0:4 offset1:6
	v_cvt_pk_bf16_f32 v16, v34, v35
	v_cvt_pk_bf16_f32 v17, v36, v37
	v_cvt_pk_bf16_f32 v56, v38, v39
	v_cvt_pk_bf16_f32 v57, v40, v41
	ds_write2_b64 v169, v[16:17], v[56:57] offset0:32 offset1:34
	v_mul_f32_e32 v56, v224, v159
	v_cmp_gt_f32_e32 vcc, s0, v56
	v_cvt_pk_bf16_f32 v16, v42, v43
	v_cvt_pk_bf16_f32 v17, v44, v45
	v_cndmask_b32_e32 v56, 0, v220, vcc
	v_fmac_f32_e32 v56, v224, v159
	v_exp_f32_e32 v65, v56
	v_cvt_pk_bf16_f32 v56, v46, v47
	v_cvt_pk_bf16_f32 v57, v48, v49
	ds_write2_b64 v169, v[16:17], v[56:57] offset0:36 offset1:38
	v_mul_f32_e32 v16, v224, v194
	v_mul_f32_e32 v3, 0x43000000, v224
	v_cndmask_b32_e32 v64, 0, v222, vcc
	v_cmp_gt_f32_e32 vcc, s0, v16
	s_lshl_b32 s62, s9, 9
	s_waitcnt vmcnt(0)
	ds_write_b128 v223, v[4:7] offset:34816
	ds_write_b128 v223, v[8:11] offset:43520
	ds_write_b128 v223, v[12:15] offset:52224
	ds_write_b128 v223, v[50:53] offset:60928
	global_load_dwordx4 v[130:133], v[54:55], off offset:256
	global_load_dwordx4 v[138:141], v[58:59], off offset:256
	global_load_dwordx4 v[146:149], v[60:61], off offset:256
	global_load_dwordx4 v[150:153], v[62:63], off offset:256
	v_cndmask_b32_e32 v16, 0, v222, vcc
	v_cndmask_b32_e32 v17, 0, v220, vcc
	v_cmp_gt_f32_e32 vcc, s0, v3
	s_lshl_b32 s55, s10, 7
	s_lshl_b32 s58, s9, 6
	v_cndmask_b32_e32 v3, 0, v220, vcc
	v_fmac_f32_e32 v3, 0x43000000, v224
	v_exp_f32_e32 v3, v3
	s_lshl_b32 s59, s10, 3
	s_lshl_b32 s66, s90, 5
	s_and_b64 s[4:5], vcc, exec
	s_cselect_b32 s4, 0xffffffc0, 0
	v_ldexp_f32 v176, v3, s4
	s_lshl_b32 s4, s8, 2
	s_lshr_b32 s5, 0x31002210, s4
	s_lshr_b32 s4, 0x33323210, s4
	s_cmpk_lt_u32 s57, 0x80
	s_cselect_b64 s[80:81], -1, 0
	s_cmpk_gt_u32 s57, 0x7f
	s_cselect_b64 s[72:73], -1, 0
	s_lshl_b32 s4, s4, 5
	s_lshl_b32 s5, s5, 5
	s_and_b32 s39, s4, 0x60
	s_lshl_b32 s4, s8, 4
	s_lshl_b32 s6, s8, 5
	s_and_b32 s5, s5, 0x60
	s_and_b32 s4, s4, 0x3fffffe0
	s_and_b32 s6, s6, 32
	s_cmpk_gt_u32 s57, 0xff
	s_cselect_b64 s[78:79], -1, 0
	s_cmpk_gt_u32 s57, 0x17f
	s_cselect_b64 s[76:77], -1, 0
	s_lshl_b64 s[60:61], s[52:53], 23
	v_fmac_f32_e32 v17, v224, v194
	s_or_b32 s60, s60, s62
	s_lshl_b64 s[68:69], s[52:53], 24
	v_exp_f32_e32 v17, v17
	s_add_u32 s62, s55, s54
	v_and_b32_e32 v8, 4, v156
	s_addc_u32 s63, 0, 0
	s_lshl_b32 s57, s56, 2
	v_or_b32_e32 v8, s5, v8
	s_or_b32 s57, s57, s59
	v_or_b32_e32 v4, s39, v1
	v_or_b32_e32 v7, s4, v201
	v_or_b32_e32 v9, 2, v8
	v_or_b32_e32 v10, 3, v8
	v_or_b32_e32 v11, 8, v8
	v_add_u32_e32 v57, s39, v199
	s_lshl_b64 s[64:65], s[90:91], 13
	s_or_b32 s57, s57, s58
	v_ldexp_f32 v174, v17, v16
	v_or_b32_e32 v3, s5, v1
	v_or_b32_e32 v5, s4, v1
	v_or_b32_e32 v6, s6, v1
	v_lshl_add_u32 v225, v7, 1, v196
	v_or_b32_e32 v7, s6, v201
	v_lshlrev_b32_e32 v227, 1, v8
	v_cmp_gt_u32_e64 s[4:5], v8, v4
	v_cmp_lt_u32_e64 s[6:7], v8, v4
	v_cmp_gt_u32_e64 s[8:9], v9, v4
	v_cmp_gt_u32_e64 s[10:11], v10, v4
	v_cmp_gt_u32_e64 s[12:13], v11, v4
	v_or_b32_e32 v12, 9, v8
	v_or_b32_e32 v13, 10, v8
	v_or_b32_e32 v14, 11, v8
	v_or_b32_e32 v15, 16, v8
	v_or_b32_e32 v16, 17, v8
	v_or_b32_e32 v17, 18, v8
	v_or_b32_e32 v50, 19, v8
	v_or_b32_e32 v51, 24, v8
	v_or_b32_e32 v52, 25, v8
	v_or_b32_e32 v53, 26, v8
	v_or_b32_e32 v54, 27, v8
	v_or_b32_e32 v56, s38, v201
	v_cmp_gt_u32_e64 s[38:39], v8, v57
	v_cmp_lt_u32_e64 s[40:41], v8, v57
	v_cmp_gt_u32_e64 s[42:43], v9, v57
	v_cmp_gt_u32_e64 s[44:45], v10, v57
	v_cmp_gt_u32_e64 s[46:47], v11, v57
	s_or_b64 s[62:63], s[62:63], s[68:69]
	s_lshl_b64 s[52:53], s[52:53], 20
	s_or_b32 s57, s64, s57
	v_or_b32_e32 v8, s66, v155
	v_or_b32_e32 v9, s66, v252
	v_or_b32_e32 v10, s66, v253
	v_or_b32_e32 v11, s66, v254
	s_add_u32 s64, s57, s52
	v_cvt_f32_u32_e32 v8, v8
	v_cvt_f32_u32_e32 v9, v9
	v_cvt_f32_u32_e32 v10, v10
	v_cvt_f32_u32_e32 v11, v11
	s_addc_u32 s65, s65, s53
	s_lshl_b32 s56, s56, 6
	s_lshl_b64 s[58:59], s[90:91], 17
	s_or_b32 s55, s56, s55
	v_cmp_gt_u32_e64 s[14:15], v12, v4
	v_cmp_gt_u32_e64 s[16:17], v13, v4
	v_cmp_gt_u32_e64 s[18:19], v14, v4
	v_cmp_gt_u32_e64 s[20:21], v15, v4
	v_cmp_gt_u32_e64 s[48:49], v12, v57
	v_cmp_gt_u32_e64 s[50:51], v13, v57
	v_cmp_gt_u32_e64 s[52:53], v14, v57
	s_add_u32 s56, s55, s54
	v_cmp_gt_u32_e64 s[54:55], v15, v57
	v_or_b32_e32 v12, s66, v198
	v_or_b32_e32 v13, s66, v206
	v_or_b32_e32 v14, s66, v207
	v_or_b32_e32 v15, s66, v208
	s_addc_u32 s57, 0, 0
	v_add_f32_e32 v228, 0xc2fe0000, v8
	v_add_f32_e32 v229, 0xc2fe0000, v9
	v_add_f32_e32 v230, 0xc2fe0000, v10
	v_add_f32_e32 v231, 0xc2fe0000, v11
	v_cvt_f32_u32_e32 v8, v12
	v_cvt_f32_u32_e32 v9, v13
	v_cvt_f32_u32_e32 v10, v14
	v_cvt_f32_u32_e32 v11, v15
	s_or_b64 s[56:57], s[56:57], s[58:59]
	s_add_u32 s68, s56, s68
	v_cmp_gt_u32_e64 s[22:23], v16, v4
	v_cmp_gt_u32_e64 s[24:25], v17, v4
	v_cmp_gt_u32_e64 s[26:27], v50, v4
	s_addc_u32 s69, s57, s69
	v_cmp_gt_u32_e64 s[56:57], v16, v57
	v_cmp_gt_u32_e64 s[58:59], v17, v57
	v_lshl_add_u64 v[178:179], s[60:61], 0, v[162:163]
	v_cmp_gt_u32_e64 s[60:61], v50, v57
	v_or_b32_e32 v16, s66, v209
	v_or_b32_e32 v17, s66, v210
	v_or_b32_e32 v50, s66, v211
	v_or_b32_e32 v59, s66, v212
	v_add_f32_e32 v232, 0xc2fe0000, v8
	v_add_f32_e32 v233, 0xc2fe0000, v9
	v_add_f32_e32 v234, 0xc2fe0000, v10
	v_add_f32_e32 v235, 0xc2fe0000, v11
	v_cvt_f32_u32_e32 v8, v16
	v_cvt_f32_u32_e32 v9, v17
	v_cvt_f32_u32_e32 v10, v50
	v_cvt_f32_u32_e32 v11, v59
	v_or_b32_e32 v60, s66, v213
	v_or_b32_e32 v61, s66, v214
	v_or_b32_e32 v62, s66, v215
	v_or_b32_e32 v63, s66, v216
	v_add_f32_e32 v236, 0xc2fe0000, v8
	v_add_f32_e32 v237, 0xc2fe0000, v9
	v_add_f32_e32 v238, 0xc2fe0000, v10
	v_add_f32_e32 v239, 0xc2fe0000, v11
	v_cvt_f32_u32_e32 v8, v60
	v_cvt_f32_u32_e32 v9, v61
	v_cvt_f32_u32_e32 v10, v62
	v_cvt_f32_u32_e32 v11, v63
	v_or_b32_e32 v55, s66, v1
	v_ldexp_f32 v172, v65, v64
	v_mul_u32_u24_e32 v3, 0x110, v3
	v_mad_u32_u24 v171, v4, s93, 0
	v_mul_lo_u32 v5, v5, s93
	v_mul_u32_u24_e32 v6, 0x210, v6
	v_lshlrev_b32_e32 v7, 1, v7
	v_cmp_gt_u32_e64 s[28:29], v51, v4
	v_cmp_gt_u32_e64 s[30:31], v52, v4
	v_cmp_gt_u32_e64 s[34:35], v53, v4
	v_cmp_gt_u32_e64 s[36:37], v54, v4
	v_add_u32_e32 v4, 0, v227
	v_mul_lo_u32 v55, v55, s93
	v_lshlrev_b32_e32 v56, 1, v56
	v_mul_u32_u24_e32 v58, 0x110, v57
	s_mov_b32 s85, 32
	v_add_u32_e32 v226, 0x8800, v225
	v_lshl_add_u64 v[180:181], s[62:63], 0, v[164:165]
	v_cmp_gt_u32_e64 s[62:63], v51, v57
	v_lshl_add_u64 v[182:183], s[64:65], 0, v[160:161]
	v_cmp_gt_u32_e64 s[64:65], v52, v57
	v_lshl_add_u64 v[184:185], s[68:69], 0, v[166:167]
	v_cmp_gt_u32_e64 s[66:67], v53, v57
	v_mov_b32_e32 v173, v172
	v_mov_b32_e32 v186, v172
	v_mov_b32_e32 v187, v172
	v_mov_b32_e32 v175, v174
	v_mov_b32_e32 v188, v174
	v_mov_b32_e32 v189, v174
	v_add_f32_e32 v240, 0xc2fe0000, v8
	v_add_f32_e32 v241, 0xc2fe0000, v9
	v_add_f32_e32 v242, 0xc2fe0000, v10
	v_add_f32_e32 v243, 0xc2fe0000, v11
	v_mov_b32_e32 v190, v176
	v_mov_b32_e32 v191, v176
	v_add_u32_e32 v244, v4, v58
	v_add_u32_e32 v245, v195, v3
	v_add_u32_e32 v246, v195, v5
	v_add_u32_e32 v247, v217, v6
	v_add_u32_e32 v248, v197, v7
	v_add_u32_e32 v249, v195, v55
	v_add_u32_e32 v250, v200, v56
	v_cmp_gt_u32_e64 s[68:69], v54, v57
	v_lshrrev_b32_e32 v155, 6, v0
	v_lshrrev_b32_e32 v156, 8, v0
	v_add_u32_e32 v155, v155, v156
	v_mov_b32_e32 v156, 0x1dc00
	v_lshl_add_u32 v155, v155, 11, v156
	v_and_b32_e32 v156, 31, v0
	v_lshl_add_u32 v154, v156, 1, v155
	v_and_b32_e32 v157, 32, v0
	v_lshl_add_u32 v154, v157, 3, v154
	v_and_b32_e32 v160, 63, v0
	v_lshl_add_u32 v155, v160, 4, v155
	v_lshrrev_b32_e32 v161, 2, v160
	v_lshlrev_b32_e32 v161, 12, v161
	v_and_b32_e32 v162, 3, v0
	v_lshl_add_u32 v161, v162, 4, v161
	v_lshlrev_b32_e32 v156, 1, v156
	v_lshl_add_u32 v156, v157, 9, v156
	v_sub_u32_e32 v156, v161, v156
	v_add_u32_e32 v156, 0xfa00000, v156
	v_add_co_u32_e32 v184, vcc, v184, v156
	s_nop 1
	v_addc_co_u32_e32 v185, vcc, 0, v185, vcc
	v_and_b32_e32 v4, 15, v0
	v_lshrrev_b32_e32 v5, 2, v4
	v_and_b32_e32 v4, 3, v4
	v_lshlrev_b32_e32 v5, 11, v5
	v_lshl_or_b32 v4, v4, 8, v5
	v_add_u32_e32 v4, 0x200000, v4
	v_add_co_u32_e32 v182, vcc, v182, v4
	s_nop 1
	v_addc_co_u32_e32 v183, vcc, 0, v183, vcc
	v_mul_f32_e32 v198, v228, v224
	v_mul_f32_e32 v199, v229, v224
	v_mul_f32_e32 v200, v230, v224
	v_mul_f32_e32 v201, v231, v224
	v_mul_f32_e32 v206, v232, v224
	v_mul_f32_e32 v207, v233, v224
	v_mul_f32_e32 v208, v234, v224
	v_mul_f32_e32 v209, v235, v224
	v_mul_f32_e32 v210, v236, v224
	v_mul_f32_e32 v211, v237, v224
	v_mul_f32_e32 v212, v238, v224
	v_mul_f32_e32 v213, v239, v224
	v_mul_f32_e32 v214, v240, v224
	v_mul_f32_e32 v215, v241, v224
	v_mul_f32_e32 v216, v242, v224
	v_mul_f32_e32 v217, v243, v224
	v_exp_f32_e32 v198, v198
	v_exp_f32_e32 v199, v199
	v_exp_f32_e32 v200, v200
	v_exp_f32_e32 v201, v201
	v_exp_f32_e32 v206, v206
	v_exp_f32_e32 v207, v207
	v_exp_f32_e32 v208, v208
	v_exp_f32_e32 v209, v209
	v_exp_f32_e32 v210, v210
	v_exp_f32_e32 v211, v211
	v_exp_f32_e32 v212, v212
	v_exp_f32_e32 v213, v213
	v_exp_f32_e32 v214, v214
	v_exp_f32_e32 v215, v215
	v_exp_f32_e32 v216, v216
	v_exp_f32_e32 v217, v217
	v_mul_f32_e32 v228, v176, v198
	v_mul_f32_e32 v229, v176, v199
	v_mul_f32_e32 v230, v176, v200
	v_mul_f32_e32 v231, v176, v201
	v_mul_f32_e32 v232, v176, v206
	v_mul_f32_e32 v233, v176, v207
	v_mul_f32_e32 v234, v176, v208
	v_mul_f32_e32 v235, v176, v209
	v_mul_f32_e32 v236, v176, v210
	v_mul_f32_e32 v237, v176, v211
	v_mul_f32_e32 v238, v176, v212
	v_mul_f32_e32 v239, v176, v213
	v_mul_f32_e32 v240, v176, v214
	v_mul_f32_e32 v241, v176, v215
	v_mul_f32_e32 v242, v176, v216
	v_mul_f32_e32 v243, v176, v217
	s_branch .LBB0_593

.LBB0_612:
	v_lshl_add_u64 v[194:195], s[82:83], 0, v[184:185]
	v_mul_f32_e32 v8, v50, v228
	s_nop 5
	v_fmac_f32_e32 v8, v66, v198
	v_mul_f32_e32 v11, v51, v229
	v_fmac_f32_e32 v11, v67, v199
	v_mul_f32_e32 v13, v52, v230
	v_fmac_f32_e32 v13, v68, v200
	s_nop 0
	v_cvt_pk_bf16_f32 v10, v8, v11
	ds_write_b16 v154, v10
	ds_write_b16_d16_hi v154, v10 offset:64
	v_mul_f32_e32 v15, v53, v231
	v_fmac_f32_e32 v15, v69, v201
	s_nop 0
	v_cvt_pk_bf16_f32 v14, v13, v15
	ds_write_b16 v154, v14 offset:128
	ds_write_b16_d16_hi v154, v14 offset:192
	v_mul_f32_e32 v17, v54, v232
	v_fmac_f32_e32 v17, v70, v206
	v_mul_f32_e32 v51, v55, v233
	v_fmac_f32_e32 v51, v71, v207
	v_cvt_pk_bf16_f32 v50, v17, v51
	ds_write_b16 v154, v50 offset:512
	ds_write_b16_d16_hi v154, v50 offset:576
	v_mul_f32_e32 v53, v56, v234
	v_fmac_f32_e32 v53, v72, v208
	v_mul_f32_e32 v55, v57, v235
	v_fmac_f32_e32 v55, v73, v209
	s_nop 0
	v_cvt_pk_bf16_f32 v54, v53, v55
	ds_write_b16 v154, v54 offset:640
	ds_write_b16_d16_hi v154, v54 offset:704
	v_mul_f32_e32 v57, v58, v236
	v_fmac_f32_e32 v57, v74, v210
	s_nop 0
	v_mul_f32_e32 v59, v59, v237
	v_fmac_f32_e32 v59, v75, v211
	v_cvt_pk_bf16_f32 v58, v57, v59
	ds_write_b16 v154, v58 offset:1024
	ds_write_b16_d16_hi v154, v58 offset:1088
	v_mul_f32_e32 v60, v60, v238
	v_fmac_f32_e32 v60, v76, v212
	s_nop 0
	v_mul_f32_e32 v61, v61, v239
	v_fmac_f32_e32 v61, v77, v213
	v_cvt_pk_bf16_f32 v67, v60, v61
	ds_write_b16 v154, v67 offset:1152
	ds_write_b16_d16_hi v154, v67 offset:1216
	v_mul_f32_e32 v62, v62, v240
	v_fmac_f32_e32 v62, v78, v214
	s_nop 0
	v_mul_f32_e32 v63, v63, v241
	v_fmac_f32_e32 v63, v79, v215
	v_cvt_pk_bf16_f32 v69, v62, v63
	ds_write_b16 v154, v69 offset:1536
	ds_write_b16_d16_hi v154, v69 offset:1600
	v_mul_f32_e32 v7, v64, v242
	v_mul_f32_e32 v65, v65, v243
	v_fmac_f32_e32 v7, v80, v216
	v_fmac_f32_e32 v65, v81, v217
	v_cvt_pk_bf16_f32 v3, v7, v65
	ds_write_b16 v154, v3 offset:1664
	ds_write_b16_d16_hi v154, v3 offset:1728
	s_mov_b64 s[70:71], 0x10000
	v_lshl_add_u64 v[196:197], v[194:195], 0, s[70:71]
	s_waitcnt lgkmcnt(0)
	ds_read_b128 v[160:163], v155
	ds_read_b128 v[164:167], v155 offset:1024
	s_mov_b32 vcc_lo, 0xaaaaaaaa
	s_mov_b32 vcc_hi, 0xaaaaaaaa
	v_cndmask_b32_e32 v3, v8, v11, vcc
	v_cndmask_b32_e32 v4, v13, v15, vcc
	v_cndmask_b32_e32 v5, v17, v51, vcc
	v_cndmask_b32_e32 v6, v53, v55, vcc
	v_cndmask_b32_e32 v9, v57, v59, vcc
	v_cndmask_b32_e32 v10, v60, v61, vcc
	v_cndmask_b32_e32 v12, v62, v63, vcc
	v_cndmask_b32_e32 v14, v7, v65, vcc
	v_cndmask_b32_e32 v11, v11, v8, vcc
	v_cndmask_b32_e32 v15, v15, v13, vcc
	v_cndmask_b32_e32 v51, v51, v17, vcc
	v_cndmask_b32_e32 v55, v55, v53, vcc
	v_cndmask_b32_e32 v59, v59, v57, vcc
	v_cndmask_b32_e32 v61, v61, v60, vcc
	v_cndmask_b32_e32 v63, v63, v62, vcc
	v_cndmask_b32_e32 v65, v65, v7, vcc
	v_mul_f32_e32 v8, v3, v3
	v_mul_f32_e32 v13, v4, v4
	v_mul_f32_e32 v17, v5, v5
	v_mul_f32_e32 v53, v6, v6
	v_mul_f32_e32 v57, v9, v9
	v_mul_f32_e32 v60, v10, v10
	v_mul_f32_e32 v62, v12, v12
	v_mul_f32_e32 v7, v14, v14
	v_mul_f32_e32 v11, v11, v11
	v_mul_f32_e32 v15, v15, v15
	v_mul_f32_e32 v51, v51, v51
	v_mul_f32_e32 v55, v55, v55
	v_mul_f32_e32 v59, v59, v59
	v_mul_f32_e32 v61, v61, v61
	v_mul_f32_e32 v63, v63, v63
	v_mul_f32_e32 v65, v65, v65
	v_add_f32_dpp v8, v11, v8 quad_perm:[1,0,3,2] row_mask:0xf bank_mask:0xf
	v_add_f32_dpp v13, v15, v13 quad_perm:[1,0,3,2] row_mask:0xf bank_mask:0xf
	v_add_f32_dpp v17, v51, v17 quad_perm:[1,0,3,2] row_mask:0xf bank_mask:0xf
	v_add_f32_dpp v53, v55, v53 quad_perm:[1,0,3,2] row_mask:0xf bank_mask:0xf
	v_add_f32_dpp v57, v59, v57 quad_perm:[1,0,3,2] row_mask:0xf bank_mask:0xf
	v_add_f32_dpp v60, v61, v60 quad_perm:[1,0,3,2] row_mask:0xf bank_mask:0xf
	v_add_f32_dpp v62, v63, v62 quad_perm:[1,0,3,2] row_mask:0xf bank_mask:0xf
	v_add_f32_dpp v7, v65, v7 quad_perm:[1,0,3,2] row_mask:0xf bank_mask:0xf
	s_mov_b32 vcc_lo, 0xcccccccc
	s_mov_b32 vcc_hi, 0xcccccccc
	v_add_f32_dpp v8, v8, v8 quad_perm:[2,3,0,1] row_mask:0xf bank_mask:0xf
	v_add_f32_dpp v13, v13, v13 quad_perm:[2,3,0,1] row_mask:0xf bank_mask:0xf
	v_add_f32_dpp v17, v17, v17 quad_perm:[2,3,0,1] row_mask:0xf bank_mask:0xf
	v_add_f32_dpp v53, v53, v53 quad_perm:[2,3,0,1] row_mask:0xf bank_mask:0xf
	v_add_f32_dpp v57, v57, v57 quad_perm:[2,3,0,1] row_mask:0xf bank_mask:0xf
	v_add_f32_dpp v60, v60, v60 quad_perm:[2,3,0,1] row_mask:0xf bank_mask:0xf
	v_add_f32_dpp v62, v62, v62 quad_perm:[2,3,0,1] row_mask:0xf bank_mask:0xf
	v_add_f32_dpp v7, v7, v7 quad_perm:[2,3,0,1] row_mask:0xf bank_mask:0xf
	v_cndmask_b32_e32 v8, v8, v13, vcc
	v_cndmask_b32_e32 v17, v17, v53, vcc
	v_cndmask_b32_e32 v57, v57, v60, vcc
	v_cndmask_b32_e32 v62, v62, v7, vcc
	s_nop 1
	v_add_f32_dpp v16, v8, v8 row_shl:4 row_mask:0xf bank_mask:0x5
	v_add_f32_dpp v16, v17, v17 row_shr:4 row_mask:0xf bank_mask:0xa
	v_add_f32_dpp v50, v57, v57 row_shl:4 row_mask:0xf bank_mask:0x5
	v_add_f32_dpp v50, v62, v62 row_shr:4 row_mask:0xf bank_mask:0xa
	s_nop 1
	v_add_f32_dpp v12, v16, v16 row_shl:8 row_mask:0xf bank_mask:0x3
	v_add_f32_dpp v12, v50, v50 row_shr:8 row_mask:0xf bank_mask:0xc
	s_waitcnt lgkmcnt(0)
	global_store_dwordx4 v[194:195], v[160:163], off
	global_store_dwordx4 v[196:197], v[164:167], off
	v_mov_b32_e32 v14, v12
	v_lshl_add_u64 v[4:5], s[82:83], 0, v[182:183]
	s_nop 0
	v_permlane16_swap_b32_e32 v12, v14
	s_mov_b64 s[70:71], exec
	v_add_f32_e32 v12, v12, v14
	s_mov_b32 exec_lo, 0xffff
	s_mov_b32 exec_hi, 0xffff
	global_store_dword v[4:5], v12, off
	s_branch .LBB0_592
